# sc1 (write-through) stores for GEMM epilogue outputs and adaLN norm outputs, to shorten the grid barrier's L2 writeback
# baseline (speedup 1.0000x reference)
; __device__ __forceinline__ unsigned cvt_pk_bf16(float lo, float hi) { unsigned r; asm volatile("v_cvt_pk_bf16_f32 %0, %1, %2" : "=v"(r) : "v"(lo), "v"(hi)); return r; }
;     __device__ __forceinline__ void operator()(const f32x4 (&acc)[2][2][4][2], const Unit& u, int wr, int wc, int fr, int fq) const {
;     ...
;             for (int m = 0; m < 4; ++m) { bf16_t* rowp = O + (size_t)(row0 + ai * HALF + m * 16) * ldc + col0;
; #pragma unroll
;                 for (int bj = 0; bj < 2; ++bj) { f32x4 v0 = acc[ai][bj][m][0], v1 = acc[ai][bj][m][1];
;                     if (gate) { v0 = v0 * gv[bj][0]; v1 = v1 * gv[bj][1]; }
;                     if (act == 1) {
; #pragma unroll
;                         for (int e = 0; e < 4; ++e) { float a = fmaxf(v0[e], 0.f), b = fmaxf(v1[e], 0.f); v0[e] = a * a; v1[e] = b * b; } }
;                     u32x4 w; w.x = cvt_pk_bf16(v0[0], v0[1]); w.y = cvt_pk_bf16(v0[2], v0[3]); w.z = cvt_pk_bf16(v1[0], v1[1]); w.w = cvt_pk_bf16(v1[2], v1[3]);
;                     *(u32x4*)(rowp + bj * HALF) = w; } }
.LBB0_419:
	v_lshl_add_u32 v164, s60, 8, v160
	v_mad_i64_i32 v[138:139], s[14:15], v164, s76, 0
	v_lshl_add_u64 v[138:139], v[138:139], 1, s[6:7]
	v_lshl_add_u64 v[138:139], v[156:157], 1, v[138:139]
	v_cvt_pk_bf16_f32 v142, v142, v143
	v_cvt_pk_bf16_f32 v143, v144, v145
	v_cvt_pk_bf16_f32 v144, v158, v159
	v_cvt_pk_bf16_f32 v145, v140, v141
	global_store_dwordx4 v[138:139], v[142:145], off sc1
	v_pk_mul_f32 v[140:141], v[136:137], v[80:81]
	v_pk_mul_f32 v[158:159], v[130:131], v[74:75]
	v_pk_mul_f32 v[142:143], v[134:135], v[78:79]
	v_pk_mul_f32 v[144:145], v[132:133], v[76:77]
	v_cndmask_b32_e64 v136, v140, v136, s[40:41]
	v_cndmask_b32_e64 v137, v141, v137, s[40:41]
	v_cndmask_b32_e64 v134, v142, v134, s[40:41]
	v_cndmask_b32_e64 v135, v143, v135, s[40:41]
	v_cndmask_b32_e64 v132, v144, v132, s[40:41]
	v_cndmask_b32_e64 v133, v145, v133, s[40:41]
	v_cndmask_b32_e64 v130, v158, v130, s[40:41]
	s_and_b64 vcc, exec, s[44:45]
	v_cndmask_b32_e64 v131, v159, v131, s[40:41]
	s_cbranch_vccnz .LBB0_421
	v_max_f32_e32 v134, v134, v134
	v_max_f32_e32 v130, v130, v130
	v_max_f32_e32 v135, v135, v135
	v_max_f32_e32 v131, v131, v131
	v_max_f32_e32 v136, v136, v136
	v_max_f32_e32 v132, v132, v132
	v_max_f32_e32 v137, v137, v137
	v_max_f32_e32 v133, v133, v133
	v_max_f32_e32 v134, 0, v134
	v_max_f32_e32 v130, 0, v130
	v_max_f32_e32 v135, 0, v135
	v_max_f32_e32 v131, 0, v131
	v_max_f32_e32 v136, 0, v136
	v_max_f32_e32 v132, 0, v132
	v_max_f32_e32 v137, 0, v137
	v_max_f32_e32 v133, 0, v133
	v_pk_mul_f32 v[134:135], v[134:135], v[134:135]
	v_pk_mul_f32 v[136:137], v[136:137], v[136:137]
	v_pk_mul_f32 v[130:131], v[130:131], v[130:131]
	v_pk_mul_f32 v[132:133], v[132:133], v[132:133]
.LBB0_421:
	v_cvt_pk_bf16_f32 v134, v134, v135
	v_cvt_pk_bf16_f32 v135, v136, v137
	v_cvt_pk_bf16_f32 v136, v130, v131
	s_nop 0
	v_cvt_pk_bf16_f32 v137, v132, v133
	global_store_dwordx4 v[138:139], v[134:137], off offset:256 sc1
	v_pk_mul_f32 v[130:131], v[128:129], v[88:89]
	v_pk_mul_f32 v[132:133], v[126:127], v[86:87]
	v_pk_mul_f32 v[134:135], v[124:125], v[84:85]
	v_pk_mul_f32 v[136:137], v[122:123], v[82:83]
	v_cndmask_b32_e64 v128, v130, v128, s[40:41]
	v_cndmask_b32_e64 v129, v131, v129, s[40:41]
	v_cndmask_b32_e64 v126, v132, v126, s[40:41]
	v_cndmask_b32_e64 v127, v133, v127, s[40:41]
	v_cndmask_b32_e64 v124, v134, v124, s[40:41]
	v_cndmask_b32_e64 v125, v135, v125, s[40:41]
	v_cndmask_b32_e64 v130, v136, v122, s[40:41]
	s_and_b64 vcc, exec, s[44:45]
	v_cndmask_b32_e64 v131, v137, v123, s[40:41]
	s_cbranch_vccnz .LBB0_423
	v_max_f32_e32 v122, v126, v126
	v_max_f32_e32 v126, v131, v131
	v_max_f32_e32 v123, v130, v130
	v_max_f32_e32 v131, 0, v126
	v_max_f32_e32 v126, v128, v128
	v_max_f32_e32 v130, 0, v123
	v_max_f32_e32 v123, v127, v127
	v_max_f32_e32 v128, 0, v126
	v_max_f32_e32 v124, v124, v124
	v_max_f32_e32 v126, v129, v129
	v_max_f32_e32 v125, v125, v125
	v_max_f32_e32 v122, 0, v122
	v_max_f32_e32 v123, 0, v123
	v_max_f32_e32 v124, 0, v124
	v_max_f32_e32 v129, 0, v126
	v_max_f32_e32 v125, 0, v125
	v_pk_mul_f32 v[126:127], v[122:123], v[122:123]
	v_pk_mul_f32 v[128:129], v[128:129], v[128:129]
	v_pk_mul_f32 v[130:131], v[130:131], v[130:131]
	v_pk_mul_f32 v[124:125], v[124:125], v[124:125]
.LBB0_423:
	v_or_b32_e32 v122, 16, v164
	v_mad_i64_i32 v[122:123], s[14:15], v122, s76, 0
	v_lshl_add_u64 v[122:123], v[122:123], 1, s[6:7]
	v_lshl_add_u64 v[122:123], v[156:157], 1, v[122:123]
	v_cvt_pk_bf16_f32 v126, v126, v127
	v_cvt_pk_bf16_f32 v127, v128, v129
	v_cvt_pk_bf16_f32 v128, v130, v131
	v_cvt_pk_bf16_f32 v129, v124, v125
	global_store_dwordx4 v[122:123], v[126:129], off sc1
	v_pk_mul_f32 v[124:125], v[120:121], v[80:81]
	v_pk_mul_f32 v[130:131], v[114:115], v[74:75]
	v_pk_mul_f32 v[126:127], v[118:119], v[78:79]
	v_pk_mul_f32 v[128:129], v[116:117], v[76:77]
	v_cndmask_b32_e64 v120, v124, v120, s[40:41]
	v_cndmask_b32_e64 v121, v125, v121, s[40:41]
	v_cndmask_b32_e64 v118, v126, v118, s[40:41]
	v_cndmask_b32_e64 v119, v127, v119, s[40:41]
	v_cndmask_b32_e64 v116, v128, v116, s[40:41]
	v_cndmask_b32_e64 v117, v129, v117, s[40:41]
	v_cndmask_b32_e64 v114, v130, v114, s[40:41]
	s_and_b64 vcc, exec, s[44:45]
	v_cndmask_b32_e64 v115, v131, v115, s[40:41]
	s_cbranch_vccnz .LBB0_425
	v_max_f32_e32 v118, v118, v118
	v_max_f32_e32 v114, v114, v114
	v_max_f32_e32 v119, v119, v119
	v_max_f32_e32 v115, v115, v115
	v_max_f32_e32 v120, v120, v120
	v_max_f32_e32 v116, v116, v116
	v_max_f32_e32 v121, v121, v121
	v_max_f32_e32 v117, v117, v117
	v_max_f32_e32 v118, 0, v118
	v_max_f32_e32 v114, 0, v114
	v_max_f32_e32 v119, 0, v119
	v_max_f32_e32 v115, 0, v115
	v_max_f32_e32 v120, 0, v120
	v_max_f32_e32 v116, 0, v116
	v_max_f32_e32 v121, 0, v121
	v_max_f32_e32 v117, 0, v117
	v_pk_mul_f32 v[118:119], v[118:119], v[118:119]
	v_pk_mul_f32 v[120:121], v[120:121], v[120:121]
	v_pk_mul_f32 v[114:115], v[114:115], v[114:115]
	v_pk_mul_f32 v[116:117], v[116:117], v[116:117]
; __device__ __forceinline__ unsigned cvt_pk_bf16(float lo, float hi) { unsigned r; asm volatile("v_cvt_pk_bf16_f32 %0, %1, %2" : "=v"(r) : "v"(lo), "v"(hi)); return r; }
;     __device__ __forceinline__ void operator()(const f32x4 (&acc)[2][2][4][2], const Unit& u, int wr, int wc, int fr, int fq) const {
;     ...
;             for (int m = 0; m < 4; ++m) { bf16_t* rowp = O + (size_t)(row0 + ai * HALF + m * 16) * ldc + col0;
; #pragma unroll
;                 for (int bj = 0; bj < 2; ++bj) { f32x4 v0 = acc[ai][bj][m][0], v1 = acc[ai][bj][m][1];
;                     if (gate) { v0 = v0 * gv[bj][0]; v1 = v1 * gv[bj][1]; }
;                     if (act == 1) {
; #pragma unroll
;                         for (int e = 0; e < 4; ++e) { float a = fmaxf(v0[e], 0.f), b = fmaxf(v1[e], 0.f); v0[e] = a * a; v1[e] = b * b; } }
;                     u32x4 w; w.x = cvt_pk_bf16(v0[0], v0[1]); w.y = cvt_pk_bf16(v0[2], v0[3]); w.z = cvt_pk_bf16(v1[0], v1[1]); w.w = cvt_pk_bf16(v1[2], v1[3]);
;                     *(u32x4*)(rowp + bj * HALF) = w; } }
.LBB0_425:
	v_cvt_pk_bf16_f32 v118, v118, v119
	v_cvt_pk_bf16_f32 v119, v120, v121
	v_cvt_pk_bf16_f32 v120, v114, v115
	s_nop 0
	v_cvt_pk_bf16_f32 v121, v116, v117
	global_store_dwordx4 v[122:123], v[118:121], off offset:256 sc1
	v_pk_mul_f32 v[114:115], v[112:113], v[88:89]
	v_pk_mul_f32 v[116:117], v[110:111], v[86:87]
	v_pk_mul_f32 v[118:119], v[108:109], v[84:85]
	v_pk_mul_f32 v[120:121], v[106:107], v[82:83]
	v_cndmask_b32_e64 v112, v114, v112, s[40:41]
	v_cndmask_b32_e64 v113, v115, v113, s[40:41]
	v_cndmask_b32_e64 v110, v116, v110, s[40:41]
	v_cndmask_b32_e64 v111, v117, v111, s[40:41]
	v_cndmask_b32_e64 v108, v118, v108, s[40:41]
	v_cndmask_b32_e64 v109, v119, v109, s[40:41]
	v_cndmask_b32_e64 v114, v120, v106, s[40:41]
	s_and_b64 vcc, exec, s[44:45]
	v_cndmask_b32_e64 v115, v121, v107, s[40:41]
	s_cbranch_vccnz .LBB0_427
	v_max_f32_e32 v106, v110, v110
	v_max_f32_e32 v110, v115, v115
	v_max_f32_e32 v107, v114, v114
	v_max_f32_e32 v115, 0, v110
	v_max_f32_e32 v110, v112, v112
	v_max_f32_e32 v114, 0, v107
	v_max_f32_e32 v107, v111, v111
	v_max_f32_e32 v112, 0, v110
	v_max_f32_e32 v108, v108, v108
	v_max_f32_e32 v110, v113, v113
	v_max_f32_e32 v109, v109, v109
	v_max_f32_e32 v106, 0, v106
	v_max_f32_e32 v107, 0, v107
	v_max_f32_e32 v108, 0, v108
	v_max_f32_e32 v113, 0, v110
	v_max_f32_e32 v109, 0, v109
	v_pk_mul_f32 v[110:111], v[106:107], v[106:107]
	v_pk_mul_f32 v[112:113], v[112:113], v[112:113]
	v_pk_mul_f32 v[114:115], v[114:115], v[114:115]
	v_pk_mul_f32 v[108:109], v[108:109], v[108:109]
.LBB0_427:
	v_or_b32_e32 v106, 32, v164
	v_mad_i64_i32 v[106:107], s[14:15], v106, s76, 0
	v_lshl_add_u64 v[106:107], v[106:107], 1, s[6:7]
	v_lshl_add_u64 v[106:107], v[156:157], 1, v[106:107]
	v_cvt_pk_bf16_f32 v110, v110, v111
	v_cvt_pk_bf16_f32 v111, v112, v113
	v_cvt_pk_bf16_f32 v112, v114, v115
	v_cvt_pk_bf16_f32 v113, v108, v109
	global_store_dwordx4 v[106:107], v[110:113], off sc1
	v_pk_mul_f32 v[108:109], v[104:105], v[80:81]
	v_pk_mul_f32 v[114:115], v[98:99], v[74:75]
	v_pk_mul_f32 v[110:111], v[102:103], v[78:79]
	v_pk_mul_f32 v[112:113], v[100:101], v[76:77]
	v_cndmask_b32_e64 v104, v108, v104, s[40:41]
	v_cndmask_b32_e64 v105, v109, v105, s[40:41]
	v_cndmask_b32_e64 v102, v110, v102, s[40:41]
	v_cndmask_b32_e64 v103, v111, v103, s[40:41]
	v_cndmask_b32_e64 v100, v112, v100, s[40:41]
	v_cndmask_b32_e64 v101, v113, v101, s[40:41]
	v_cndmask_b32_e64 v98, v114, v98, s[40:41]
	s_and_b64 vcc, exec, s[44:45]
	v_cndmask_b32_e64 v99, v115, v99, s[40:41]
	s_cbranch_vccnz .LBB0_429
	v_max_f32_e32 v102, v102, v102
	v_max_f32_e32 v98, v98, v98
	v_max_f32_e32 v103, v103, v103
	v_max_f32_e32 v99, v99, v99
	v_max_f32_e32 v104, v104, v104
	v_max_f32_e32 v100, v100, v100
	v_max_f32_e32 v105, v105, v105
	v_max_f32_e32 v101, v101, v101
	v_max_f32_e32 v102, 0, v102
	v_max_f32_e32 v98, 0, v98
	v_max_f32_e32 v103, 0, v103
	v_max_f32_e32 v99, 0, v99
	v_max_f32_e32 v104, 0, v104
	v_max_f32_e32 v100, 0, v100
	v_max_f32_e32 v105, 0, v105
	v_max_f32_e32 v101, 0, v101
	v_pk_mul_f32 v[102:103], v[102:103], v[102:103]
	v_pk_mul_f32 v[104:105], v[104:105], v[104:105]
	v_pk_mul_f32 v[98:99], v[98:99], v[98:99]
	v_pk_mul_f32 v[100:101], v[100:101], v[100:101]
.LBB0_429:
	v_cvt_pk_bf16_f32 v102, v102, v103
	v_cvt_pk_bf16_f32 v103, v104, v105
	v_cvt_pk_bf16_f32 v104, v98, v99
	s_nop 0
	v_cvt_pk_bf16_f32 v105, v100, v101
	global_store_dwordx4 v[106:107], v[102:105], off offset:256 sc1
	v_pk_mul_f32 v[98:99], v[96:97], v[88:89]
	v_pk_mul_f32 v[100:101], v[94:95], v[86:87]
	v_pk_mul_f32 v[102:103], v[92:93], v[84:85]
	v_pk_mul_f32 v[104:105], v[90:91], v[82:83]
	v_cndmask_b32_e64 v96, v98, v96, s[40:41]
	v_cndmask_b32_e64 v97, v99, v97, s[40:41]
	v_cndmask_b32_e64 v94, v100, v94, s[40:41]
	v_cndmask_b32_e64 v95, v101, v95, s[40:41]
	v_cndmask_b32_e64 v92, v102, v92, s[40:41]
	v_cndmask_b32_e64 v93, v103, v93, s[40:41]
	v_cndmask_b32_e64 v98, v104, v90, s[40:41]
	s_and_b64 vcc, exec, s[44:45]
	v_cndmask_b32_e64 v99, v105, v91, s[40:41]
	s_cbranch_vccnz .LBB0_431
	v_max_f32_e32 v90, v94, v94
	v_max_f32_e32 v94, v99, v99
	v_max_f32_e32 v91, v98, v98
	v_max_f32_e32 v99, 0, v94
	v_max_f32_e32 v94, v96, v96
	v_max_f32_e32 v98, 0, v91
	v_max_f32_e32 v91, v95, v95
	v_max_f32_e32 v96, 0, v94
	v_max_f32_e32 v92, v92, v92
	v_max_f32_e32 v94, v97, v97
	v_max_f32_e32 v93, v93, v93
	v_max_f32_e32 v90, 0, v90
	v_max_f32_e32 v91, 0, v91
	v_max_f32_e32 v92, 0, v92
	v_max_f32_e32 v97, 0, v94
	v_max_f32_e32 v93, 0, v93
	v_pk_mul_f32 v[94:95], v[90:91], v[90:91]
	v_pk_mul_f32 v[96:97], v[96:97], v[96:97]
	v_pk_mul_f32 v[98:99], v[98:99], v[98:99]
	v_pk_mul_f32 v[92:93], v[92:93], v[92:93]
.LBB0_431:
	v_or_b32_e32 v90, 48, v164
	v_mad_i64_i32 v[90:91], s[14:15], v90, s76, 0
	v_lshl_add_u64 v[90:91], v[90:91], 1, s[6:7]
	v_lshl_add_u64 v[90:91], v[156:157], 1, v[90:91]
	v_cvt_pk_bf16_f32 v94, v94, v95
	v_cvt_pk_bf16_f32 v95, v96, v97
	v_cvt_pk_bf16_f32 v96, v98, v99
	v_cvt_pk_bf16_f32 v97, v92, v93
	global_store_dwordx4 v[90:91], v[94:97], off sc1
	v_pk_mul_f32 v[92:93], v[72:73], v[80:81]
	v_pk_mul_f32 v[98:99], v[66:67], v[74:75]
	v_pk_mul_f32 v[94:95], v[70:71], v[78:79]
	v_pk_mul_f32 v[96:97], v[68:69], v[76:77]
	v_cndmask_b32_e64 v72, v92, v72, s[40:41]
	v_cndmask_b32_e64 v73, v93, v73, s[40:41]
	v_cndmask_b32_e64 v70, v94, v70, s[40:41]
	v_cndmask_b32_e64 v71, v95, v71, s[40:41]
	v_cndmask_b32_e64 v68, v96, v68, s[40:41]
	v_cndmask_b32_e64 v69, v97, v69, s[40:41]
	v_cndmask_b32_e64 v66, v98, v66, s[40:41]
	s_and_b64 vcc, exec, s[44:45]
	v_cndmask_b32_e64 v67, v99, v67, s[40:41]
	s_cbranch_vccnz .LBB0_433
	v_max_f32_e32 v70, v70, v70
	v_max_f32_e32 v66, v66, v66
	v_max_f32_e32 v71, v71, v71
	v_max_f32_e32 v67, v67, v67
	v_max_f32_e32 v72, v72, v72
	v_max_f32_e32 v68, v68, v68
	v_max_f32_e32 v73, v73, v73
	v_max_f32_e32 v69, v69, v69
	v_max_f32_e32 v70, 0, v70
	v_max_f32_e32 v66, 0, v66
	v_max_f32_e32 v71, 0, v71
	v_max_f32_e32 v67, 0, v67
	v_max_f32_e32 v72, 0, v72
	v_max_f32_e32 v68, 0, v68
	v_max_f32_e32 v73, 0, v73
	v_max_f32_e32 v69, 0, v69
	v_pk_mul_f32 v[70:71], v[70:71], v[70:71]
	v_pk_mul_f32 v[72:73], v[72:73], v[72:73]
	v_pk_mul_f32 v[66:67], v[66:67], v[66:67]
	v_pk_mul_f32 v[68:69], v[68:69], v[68:69]
; __device__ __forceinline__ unsigned cvt_pk_bf16(float lo, float hi) { unsigned r; asm volatile("v_cvt_pk_bf16_f32 %0, %1, %2" : "=v"(r) : "v"(lo), "v"(hi)); return r; }
;     __device__ __forceinline__ void operator()(const f32x4 (&acc)[2][2][4][2], const Unit& u, int wr, int wc, int fr, int fq) const {
;     ...
;             for (int m = 0; m < 4; ++m) { bf16_t* rowp = O + (size_t)(row0 + ai * HALF + m * 16) * ldc + col0;
; #pragma unroll
;                 for (int bj = 0; bj < 2; ++bj) { f32x4 v0 = acc[ai][bj][m][0], v1 = acc[ai][bj][m][1];
;                     if (gate) { v0 = v0 * gv[bj][0]; v1 = v1 * gv[bj][1]; }
;                     if (act == 1) {
; #pragma unroll
;                         for (int e = 0; e < 4; ++e) { float a = fmaxf(v0[e], 0.f), b = fmaxf(v1[e], 0.f); v0[e] = a * a; v1[e] = b * b; } }
;                     u32x4 w; w.x = cvt_pk_bf16(v0[0], v0[1]); w.y = cvt_pk_bf16(v0[2], v0[3]); w.z = cvt_pk_bf16(v1[0], v1[1]); w.w = cvt_pk_bf16(v1[2], v1[3]);
;                     *(u32x4*)(rowp + bj * HALF) = w; } }
.LBB0_433:
	v_cvt_pk_bf16_f32 v70, v70, v71
	v_cvt_pk_bf16_f32 v71, v72, v73
	v_cvt_pk_bf16_f32 v72, v66, v67
	s_nop 0
	v_cvt_pk_bf16_f32 v73, v68, v69
	global_store_dwordx4 v[90:91], v[70:73], off offset:256 sc1
	v_pk_mul_f32 v[66:67], v[64:65], v[88:89]
	v_pk_mul_f32 v[68:69], v[62:63], v[86:87]
	v_pk_mul_f32 v[70:71], v[60:61], v[84:85]
	v_pk_mul_f32 v[72:73], v[58:59], v[82:83]
	v_cndmask_b32_e64 v64, v66, v64, s[40:41]
	v_cndmask_b32_e64 v65, v67, v65, s[40:41]
	v_cndmask_b32_e64 v62, v68, v62, s[40:41]
	v_cndmask_b32_e64 v63, v69, v63, s[40:41]
	v_cndmask_b32_e64 v60, v70, v60, s[40:41]
	v_cndmask_b32_e64 v61, v71, v61, s[40:41]
	v_cndmask_b32_e64 v66, v72, v58, s[40:41]
	s_and_b64 vcc, exec, s[44:45]
	v_cndmask_b32_e64 v67, v73, v59, s[40:41]
	s_cbranch_vccnz .LBB0_435
	v_max_f32_e32 v58, v62, v62
	v_max_f32_e32 v62, v67, v67
	v_max_f32_e32 v59, v66, v66
	v_max_f32_e32 v67, 0, v62
	v_max_f32_e32 v62, v64, v64
	v_max_f32_e32 v66, 0, v59
	v_max_f32_e32 v59, v63, v63
	v_max_f32_e32 v64, 0, v62
	v_max_f32_e32 v60, v60, v60
	v_max_f32_e32 v62, v65, v65
	v_max_f32_e32 v61, v61, v61
	v_max_f32_e32 v58, 0, v58
	v_max_f32_e32 v59, 0, v59
	v_max_f32_e32 v60, 0, v60
	v_max_f32_e32 v65, 0, v62
	v_max_f32_e32 v61, 0, v61
	v_pk_mul_f32 v[62:63], v[58:59], v[58:59]
	v_pk_mul_f32 v[64:65], v[64:65], v[64:65]
	v_pk_mul_f32 v[66:67], v[66:67], v[66:67]
	v_pk_mul_f32 v[60:61], v[60:61], v[60:61]
.LBB0_435:
	v_add_u32_e32 v58, 0x80, v164
	v_mad_i64_i32 v[58:59], s[14:15], v58, s76, 0
	v_lshl_add_u64 v[58:59], v[58:59], 1, s[6:7]
	v_lshl_add_u64 v[58:59], v[156:157], 1, v[58:59]
	v_cvt_pk_bf16_f32 v62, v62, v63
	v_cvt_pk_bf16_f32 v63, v64, v65
	v_cvt_pk_bf16_f32 v64, v66, v67
	v_cvt_pk_bf16_f32 v65, v60, v61
	global_store_dwordx4 v[58:59], v[62:65], off sc1
	v_pk_mul_f32 v[60:61], v[56:57], v[80:81]
	v_pk_mul_f32 v[66:67], v[50:51], v[74:75]
	v_pk_mul_f32 v[62:63], v[54:55], v[78:79]
	v_pk_mul_f32 v[64:65], v[52:53], v[76:77]
	v_cndmask_b32_e64 v56, v60, v56, s[40:41]
	v_cndmask_b32_e64 v57, v61, v57, s[40:41]
	v_cndmask_b32_e64 v54, v62, v54, s[40:41]
	v_cndmask_b32_e64 v55, v63, v55, s[40:41]
	v_cndmask_b32_e64 v52, v64, v52, s[40:41]
	v_cndmask_b32_e64 v53, v65, v53, s[40:41]
	v_cndmask_b32_e64 v50, v66, v50, s[40:41]
	s_and_b64 vcc, exec, s[44:45]
	v_cndmask_b32_e64 v51, v67, v51, s[40:41]
	s_cbranch_vccnz .LBB0_437
	v_max_f32_e32 v54, v54, v54
	v_max_f32_e32 v50, v50, v50
	v_max_f32_e32 v55, v55, v55
	v_max_f32_e32 v51, v51, v51
	v_max_f32_e32 v56, v56, v56
	v_max_f32_e32 v52, v52, v52
	v_max_f32_e32 v57, v57, v57
	v_max_f32_e32 v53, v53, v53
	v_max_f32_e32 v54, 0, v54
	v_max_f32_e32 v50, 0, v50
	v_max_f32_e32 v55, 0, v55
	v_max_f32_e32 v51, 0, v51
	v_max_f32_e32 v56, 0, v56
	v_max_f32_e32 v52, 0, v52
	v_max_f32_e32 v57, 0, v57
	v_max_f32_e32 v53, 0, v53
	v_pk_mul_f32 v[54:55], v[54:55], v[54:55]
	v_pk_mul_f32 v[56:57], v[56:57], v[56:57]
	v_pk_mul_f32 v[50:51], v[50:51], v[50:51]
	v_pk_mul_f32 v[52:53], v[52:53], v[52:53]
.LBB0_437:
	v_cvt_pk_bf16_f32 v54, v54, v55
	v_cvt_pk_bf16_f32 v55, v56, v57
	v_cvt_pk_bf16_f32 v56, v50, v51
	s_nop 0
	v_cvt_pk_bf16_f32 v57, v52, v53
	global_store_dwordx4 v[58:59], v[54:57], off offset:256 sc1
	v_pk_mul_f32 v[50:51], v[48:49], v[88:89]
	v_pk_mul_f32 v[52:53], v[46:47], v[86:87]
	v_pk_mul_f32 v[54:55], v[44:45], v[84:85]
	v_pk_mul_f32 v[56:57], v[42:43], v[82:83]
	v_cndmask_b32_e64 v48, v50, v48, s[40:41]
	v_cndmask_b32_e64 v49, v51, v49, s[40:41]
	v_cndmask_b32_e64 v46, v52, v46, s[40:41]
	v_cndmask_b32_e64 v47, v53, v47, s[40:41]
	v_cndmask_b32_e64 v44, v54, v44, s[40:41]
	v_cndmask_b32_e64 v45, v55, v45, s[40:41]
	v_cndmask_b32_e64 v50, v56, v42, s[40:41]
	s_and_b64 vcc, exec, s[44:45]
	v_cndmask_b32_e64 v51, v57, v43, s[40:41]
	s_cbranch_vccnz .LBB0_439
	v_max_f32_e32 v42, v46, v46
	v_max_f32_e32 v46, v51, v51
	v_max_f32_e32 v43, v50, v50
	v_max_f32_e32 v51, 0, v46
	v_max_f32_e32 v46, v48, v48
	v_max_f32_e32 v50, 0, v43
	v_max_f32_e32 v43, v47, v47
	v_max_f32_e32 v48, 0, v46
	v_max_f32_e32 v44, v44, v44
	v_max_f32_e32 v46, v49, v49
	v_max_f32_e32 v45, v45, v45
	v_max_f32_e32 v42, 0, v42
	v_max_f32_e32 v43, 0, v43
	v_max_f32_e32 v44, 0, v44
	v_max_f32_e32 v49, 0, v46
	v_max_f32_e32 v45, 0, v45
	v_pk_mul_f32 v[46:47], v[42:43], v[42:43]
	v_pk_mul_f32 v[48:49], v[48:49], v[48:49]
	v_pk_mul_f32 v[50:51], v[50:51], v[50:51]
	v_pk_mul_f32 v[44:45], v[44:45], v[44:45]
.LBB0_439:
	v_add_u32_e32 v42, 0x90, v164
	v_mad_i64_i32 v[42:43], s[14:15], v42, s76, 0
	v_lshl_add_u64 v[42:43], v[42:43], 1, s[6:7]
	v_lshl_add_u64 v[42:43], v[156:157], 1, v[42:43]
	v_cvt_pk_bf16_f32 v46, v46, v47
	v_cvt_pk_bf16_f32 v47, v48, v49
	v_cvt_pk_bf16_f32 v48, v50, v51
	v_cvt_pk_bf16_f32 v49, v44, v45
	global_store_dwordx4 v[42:43], v[46:49], off sc1
	v_pk_mul_f32 v[44:45], v[40:41], v[80:81]
	v_pk_mul_f32 v[50:51], v[34:35], v[74:75]
	v_pk_mul_f32 v[46:47], v[38:39], v[78:79]
	v_pk_mul_f32 v[48:49], v[36:37], v[76:77]
	v_cndmask_b32_e64 v40, v44, v40, s[40:41]
	v_cndmask_b32_e64 v41, v45, v41, s[40:41]
	v_cndmask_b32_e64 v38, v46, v38, s[40:41]
	v_cndmask_b32_e64 v39, v47, v39, s[40:41]
	v_cndmask_b32_e64 v36, v48, v36, s[40:41]
	v_cndmask_b32_e64 v37, v49, v37, s[40:41]
	v_cndmask_b32_e64 v34, v50, v34, s[40:41]
	s_and_b64 vcc, exec, s[44:45]
	v_cndmask_b32_e64 v35, v51, v35, s[40:41]
	s_cbranch_vccnz .LBB0_441
	v_max_f32_e32 v38, v38, v38
	v_max_f32_e32 v34, v34, v34
	v_max_f32_e32 v39, v39, v39
	v_max_f32_e32 v35, v35, v35
	v_max_f32_e32 v40, v40, v40
	v_max_f32_e32 v36, v36, v36
	v_max_f32_e32 v41, v41, v41
	v_max_f32_e32 v37, v37, v37
	v_max_f32_e32 v38, 0, v38
	v_max_f32_e32 v34, 0, v34
	v_max_f32_e32 v39, 0, v39
	v_max_f32_e32 v35, 0, v35
	v_max_f32_e32 v40, 0, v40
	v_max_f32_e32 v36, 0, v36
	v_max_f32_e32 v41, 0, v41
	v_max_f32_e32 v37, 0, v37
	v_pk_mul_f32 v[38:39], v[38:39], v[38:39]
	v_pk_mul_f32 v[40:41], v[40:41], v[40:41]
	v_pk_mul_f32 v[34:35], v[34:35], v[34:35]
	v_pk_mul_f32 v[36:37], v[36:37], v[36:37]
; __device__ __forceinline__ unsigned cvt_pk_bf16(float lo, float hi) { unsigned r; asm volatile("v_cvt_pk_bf16_f32 %0, %1, %2" : "=v"(r) : "v"(lo), "v"(hi)); return r; }
;     __device__ __forceinline__ void operator()(const f32x4 (&acc)[2][2][4][2], const Unit& u, int wr, int wc, int fr, int fq) const {
;     ...
;             for (int m = 0; m < 4; ++m) { bf16_t* rowp = O + (size_t)(row0 + ai * HALF + m * 16) * ldc + col0;
; #pragma unroll
;                 for (int bj = 0; bj < 2; ++bj) { f32x4 v0 = acc[ai][bj][m][0], v1 = acc[ai][bj][m][1];
;                     if (gate) { v0 = v0 * gv[bj][0]; v1 = v1 * gv[bj][1]; }
;                     if (act == 1) {
; #pragma unroll
;                         for (int e = 0; e < 4; ++e) { float a = fmaxf(v0[e], 0.f), b = fmaxf(v1[e], 0.f); v0[e] = a * a; v1[e] = b * b; } }
;                     u32x4 w; w.x = cvt_pk_bf16(v0[0], v0[1]); w.y = cvt_pk_bf16(v0[2], v0[3]); w.z = cvt_pk_bf16(v1[0], v1[1]); w.w = cvt_pk_bf16(v1[2], v1[3]);
;                     *(u32x4*)(rowp + bj * HALF) = w; } }
.LBB0_441:
	v_cvt_pk_bf16_f32 v38, v38, v39
	v_cvt_pk_bf16_f32 v39, v40, v41
	v_cvt_pk_bf16_f32 v40, v34, v35
	s_nop 0
	v_cvt_pk_bf16_f32 v41, v36, v37
	global_store_dwordx4 v[42:43], v[38:41], off offset:256 sc1
	v_pk_mul_f32 v[34:35], v[32:33], v[88:89]
	v_pk_mul_f32 v[36:37], v[30:31], v[86:87]
	v_pk_mul_f32 v[38:39], v[28:29], v[84:85]
	v_pk_mul_f32 v[40:41], v[26:27], v[82:83]
	v_cndmask_b32_e64 v32, v34, v32, s[40:41]
	v_cndmask_b32_e64 v33, v35, v33, s[40:41]
	v_cndmask_b32_e64 v30, v36, v30, s[40:41]
	v_cndmask_b32_e64 v31, v37, v31, s[40:41]
	v_cndmask_b32_e64 v28, v38, v28, s[40:41]
	v_cndmask_b32_e64 v29, v39, v29, s[40:41]
	v_cndmask_b32_e64 v34, v40, v26, s[40:41]
	s_and_b64 vcc, exec, s[44:45]
	v_cndmask_b32_e64 v35, v41, v27, s[40:41]
	s_cbranch_vccnz .LBB0_443
	v_max_f32_e32 v26, v30, v30
	v_max_f32_e32 v30, v35, v35
	v_max_f32_e32 v27, v34, v34
	v_max_f32_e32 v35, 0, v30
	v_max_f32_e32 v30, v32, v32
	v_max_f32_e32 v34, 0, v27
	v_max_f32_e32 v27, v31, v31
	v_max_f32_e32 v32, 0, v30
	v_max_f32_e32 v28, v28, v28
	v_max_f32_e32 v30, v33, v33
	v_max_f32_e32 v29, v29, v29
	v_max_f32_e32 v26, 0, v26
	v_max_f32_e32 v27, 0, v27
	v_max_f32_e32 v28, 0, v28
	v_max_f32_e32 v33, 0, v30
	v_max_f32_e32 v29, 0, v29
	v_pk_mul_f32 v[30:31], v[26:27], v[26:27]
	v_pk_mul_f32 v[32:33], v[32:33], v[32:33]
	v_pk_mul_f32 v[34:35], v[34:35], v[34:35]
	v_pk_mul_f32 v[28:29], v[28:29], v[28:29]
.LBB0_443:
	v_add_u32_e32 v26, 0xa0, v164
	v_mad_i64_i32 v[26:27], s[14:15], v26, s76, 0
	v_lshl_add_u64 v[26:27], v[26:27], 1, s[6:7]
	v_lshl_add_u64 v[26:27], v[156:157], 1, v[26:27]
	v_cvt_pk_bf16_f32 v30, v30, v31
	v_cvt_pk_bf16_f32 v31, v32, v33
	v_cvt_pk_bf16_f32 v32, v34, v35
	v_cvt_pk_bf16_f32 v33, v28, v29
	global_store_dwordx4 v[26:27], v[30:33], off sc1
	v_pk_mul_f32 v[28:29], v[24:25], v[80:81]
	v_pk_mul_f32 v[34:35], v[18:19], v[74:75]
	v_pk_mul_f32 v[30:31], v[22:23], v[78:79]
	v_pk_mul_f32 v[32:33], v[20:21], v[76:77]
	v_cndmask_b32_e64 v24, v28, v24, s[40:41]
	v_cndmask_b32_e64 v25, v29, v25, s[40:41]
	v_cndmask_b32_e64 v22, v30, v22, s[40:41]
	v_cndmask_b32_e64 v23, v31, v23, s[40:41]
	v_cndmask_b32_e64 v20, v32, v20, s[40:41]
	v_cndmask_b32_e64 v21, v33, v21, s[40:41]
	v_cndmask_b32_e64 v18, v34, v18, s[40:41]
	s_and_b64 vcc, exec, s[44:45]
	v_cndmask_b32_e64 v19, v35, v19, s[40:41]
	s_cbranch_vccnz .LBB0_445
	v_max_f32_e32 v22, v22, v22
	v_max_f32_e32 v18, v18, v18
	v_max_f32_e32 v23, v23, v23
	v_max_f32_e32 v19, v19, v19
	v_max_f32_e32 v24, v24, v24
	v_max_f32_e32 v20, v20, v20
	v_max_f32_e32 v25, v25, v25
	v_max_f32_e32 v21, v21, v21
	v_max_f32_e32 v22, 0, v22
	v_max_f32_e32 v18, 0, v18
	v_max_f32_e32 v23, 0, v23
	v_max_f32_e32 v19, 0, v19
	v_max_f32_e32 v24, 0, v24
	v_max_f32_e32 v20, 0, v20
	v_max_f32_e32 v25, 0, v25
	v_max_f32_e32 v21, 0, v21
	v_pk_mul_f32 v[22:23], v[22:23], v[22:23]
	v_pk_mul_f32 v[24:25], v[24:25], v[24:25]
	v_pk_mul_f32 v[18:19], v[18:19], v[18:19]
	v_pk_mul_f32 v[20:21], v[20:21], v[20:21]
.LBB0_445:
	v_cvt_pk_bf16_f32 v22, v22, v23
	v_cvt_pk_bf16_f32 v23, v24, v25
	v_cvt_pk_bf16_f32 v24, v18, v19
	s_nop 0
	v_cvt_pk_bf16_f32 v25, v20, v21
	global_store_dwordx4 v[26:27], v[22:25], off offset:256 sc1
	v_pk_mul_f32 v[18:19], v[16:17], v[88:89]
	v_pk_mul_f32 v[20:21], v[14:15], v[86:87]
	v_pk_mul_f32 v[22:23], v[12:13], v[84:85]
	v_pk_mul_f32 v[24:25], v[10:11], v[82:83]
	v_cndmask_b32_e64 v16, v18, v16, s[40:41]
	v_cndmask_b32_e64 v17, v19, v17, s[40:41]
	v_cndmask_b32_e64 v14, v20, v14, s[40:41]
	v_cndmask_b32_e64 v15, v21, v15, s[40:41]
	v_cndmask_b32_e64 v12, v22, v12, s[40:41]
	v_cndmask_b32_e64 v13, v23, v13, s[40:41]
	v_cndmask_b32_e64 v18, v24, v10, s[40:41]
	s_and_b64 vcc, exec, s[44:45]
	v_cndmask_b32_e64 v19, v25, v11, s[40:41]
	s_cbranch_vccnz .LBB0_447
	v_max_f32_e32 v10, v14, v14
	v_max_f32_e32 v14, v19, v19
	v_max_f32_e32 v11, v18, v18
	v_max_f32_e32 v19, 0, v14
	v_max_f32_e32 v14, v16, v16
	v_max_f32_e32 v18, 0, v11
	v_max_f32_e32 v11, v15, v15
	v_max_f32_e32 v16, 0, v14
	v_max_f32_e32 v12, v12, v12
	v_max_f32_e32 v14, v17, v17
	v_max_f32_e32 v13, v13, v13
	v_max_f32_e32 v10, 0, v10
	v_max_f32_e32 v11, 0, v11
	v_max_f32_e32 v12, 0, v12
	v_max_f32_e32 v17, 0, v14
	v_max_f32_e32 v13, 0, v13
	v_pk_mul_f32 v[14:15], v[10:11], v[10:11]
	v_pk_mul_f32 v[16:17], v[16:17], v[16:17]
	v_pk_mul_f32 v[18:19], v[18:19], v[18:19]
	v_pk_mul_f32 v[12:13], v[12:13], v[12:13]
.LBB0_447:
	v_add_u32_e32 v10, 0xb0, v164
	v_mad_i64_i32 v[10:11], s[14:15], v10, s76, 0
	v_lshl_add_u64 v[10:11], v[10:11], 1, s[6:7]
	v_lshl_add_u64 v[10:11], v[156:157], 1, v[10:11]
	v_cvt_pk_bf16_f32 v14, v14, v15
	v_cvt_pk_bf16_f32 v15, v16, v17
	v_cvt_pk_bf16_f32 v16, v18, v19
	v_cvt_pk_bf16_f32 v17, v12, v13
	global_store_dwordx4 v[10:11], v[14:17], off sc1
	v_pk_mul_f32 v[12:13], v[8:9], v[80:81]
	v_pk_mul_f32 v[18:19], v[2:3], v[74:75]
	v_pk_mul_f32 v[14:15], v[6:7], v[78:79]
	v_pk_mul_f32 v[16:17], v[4:5], v[76:77]
	v_cndmask_b32_e64 v8, v12, v8, s[40:41]
	v_cndmask_b32_e64 v9, v13, v9, s[40:41]
	v_cndmask_b32_e64 v6, v14, v6, s[40:41]
	v_cndmask_b32_e64 v7, v15, v7, s[40:41]
	v_cndmask_b32_e64 v4, v16, v4, s[40:41]
	v_cndmask_b32_e64 v5, v17, v5, s[40:41]
	v_cndmask_b32_e64 v2, v18, v2, s[40:41]
	s_and_b64 vcc, exec, s[44:45]
	v_cndmask_b32_e64 v3, v19, v3, s[40:41]
	s_cbranch_vccnz .LBB0_449
	v_max_f32_e32 v6, v6, v6
	v_max_f32_e32 v2, v2, v2
	v_max_f32_e32 v7, v7, v7
	v_max_f32_e32 v3, v3, v3
	v_max_f32_e32 v8, v8, v8
	v_max_f32_e32 v4, v4, v4
	v_max_f32_e32 v9, v9, v9
	v_max_f32_e32 v5, v5, v5
	v_max_f32_e32 v6, 0, v6
	v_max_f32_e32 v2, 0, v2
	v_max_f32_e32 v7, 0, v7
	v_max_f32_e32 v3, 0, v3
	v_max_f32_e32 v8, 0, v8
	v_max_f32_e32 v4, 0, v4
	v_max_f32_e32 v9, 0, v9
	v_max_f32_e32 v5, 0, v5
	v_pk_mul_f32 v[6:7], v[6:7], v[6:7]
	v_pk_mul_f32 v[8:9], v[8:9], v[8:9]
	v_pk_mul_f32 v[2:3], v[2:3], v[2:3]
	v_pk_mul_f32 v[4:5], v[4:5], v[4:5]
.LBB0_449:
	s_andn2_b64 vcc, exec, s[42:43]
	s_mov_b64 s[14:15], -1
	v_cvt_pk_bf16_f32 v6, v6, v7
	v_cvt_pk_bf16_f32 v7, v8, v9
	v_cvt_pk_bf16_f32 v8, v2, v3
	v_cvt_pk_bf16_f32 v9, v4, v5
	global_store_dwordx4 v[10:11], v[6:9], off offset:256 sc1

; __device__ __forceinline__ unsigned cvt_pk_bf16(float lo, float hi) { unsigned r; asm volatile("v_cvt_pk_bf16_f32 %0, %1, %2" : "=v"(r) : "v"(lo), "v"(hi)); return r; }
;     __device__ __forceinline__ void operator()(const f32x4 (&acc)[2][2][4][2], const Unit& u, int wr, int wc, int fr, int fq) const {
;     ...
;             for (int m = 0; m < 4; ++m) { bf16_t* rowp = O + (size_t)(row0 + ai * HALF + m * 16) * ldc + col0;
; #pragma unroll
;                 for (int bj = 0; bj < 2; ++bj) { f32x4 v0 = acc[ai][bj][m][0], v1 = acc[ai][bj][m][1];
;                     if (gate) { v0 = v0 * gv[bj][0]; v1 = v1 * gv[bj][1]; }
;                     if (act == 1) {
; #pragma unroll
;                         for (int e = 0; e < 4; ++e) { float a = fmaxf(v0[e], 0.f), b = fmaxf(v1[e], 0.f); v0[e] = a * a; v1[e] = b * b; } }
;                     u32x4 w; w.x = cvt_pk_bf16(v0[0], v0[1]); w.y = cvt_pk_bf16(v0[2], v0[3]); w.z = cvt_pk_bf16(v1[0], v1[1]); w.w = cvt_pk_bf16(v1[2], v1[3]);
;                     *(u32x4*)(rowp + bj * HALF) = w; } }
.Lepi_lean:
	v_mul_lo_u32 v164, v160, s76
	s_lshl_b32 s14, s60, 8
	s_mul_hi_u32 s15, s14, s76
	s_mul_i32 s14, s14, s76
	s_lshl_b32 s100, s44, 8
	s_add_u32 s14, s14, s100
	s_addc_u32 s15, s15, 0
	s_lshl_b64 s[14:15], s[14:15], 1
	s_add_u32 s100, s6, s14
	s_addc_u32 s101, s7, s15
	s_lshl_b32 s14, s76, 5
	s_mul_i32 s15, s14, 5
	v_add_lshl_u32 v164, v164, v162, 1
	s_andn2_b64 vcc, exec, s[38:39]
	s_cbranch_vccnz .Lepi_lean_noact
	v_max_f32_e32 v142, 0, v142
	v_max_f32_e32 v143, 0, v143
	v_max_f32_e32 v144, 0, v144
	v_max_f32_e32 v145, 0, v145
	v_max_f32_e32 v138, 0, v138
	v_max_f32_e32 v139, 0, v139
	v_max_f32_e32 v140, 0, v140
	v_max_f32_e32 v141, 0, v141
	v_mul_f32_e32 v142, v142, v142
	v_mul_f32_e32 v143, v143, v143
	v_mul_f32_e32 v144, v144, v144
	v_mul_f32_e32 v145, v145, v145
	v_mul_f32_e32 v138, v138, v138
	v_mul_f32_e32 v139, v139, v139
	v_mul_f32_e32 v140, v140, v140
	v_mul_f32_e32 v141, v141, v141
	v_cvt_pk_bf16_f32 v142, v142, v143
	v_cvt_pk_bf16_f32 v143, v144, v145
	v_cvt_pk_bf16_f32 v144, v138, v139
	v_cvt_pk_bf16_f32 v145, v140, v141
	global_store_dwordx4 v164, v[142:145], s[100:101] sc1
	v_max_f32_e32 v134, 0, v134
	v_max_f32_e32 v135, 0, v135
	v_max_f32_e32 v136, 0, v136
	v_max_f32_e32 v137, 0, v137
	v_max_f32_e32 v130, 0, v130
	v_max_f32_e32 v131, 0, v131
	v_max_f32_e32 v132, 0, v132
	v_max_f32_e32 v133, 0, v133
	v_mul_f32_e32 v134, v134, v134
	v_mul_f32_e32 v135, v135, v135
	v_mul_f32_e32 v136, v136, v136
	v_mul_f32_e32 v137, v137, v137
	v_mul_f32_e32 v130, v130, v130
	v_mul_f32_e32 v131, v131, v131
	v_mul_f32_e32 v132, v132, v132
	v_mul_f32_e32 v133, v133, v133
	v_cvt_pk_bf16_f32 v134, v134, v135
	v_cvt_pk_bf16_f32 v135, v136, v137
	v_cvt_pk_bf16_f32 v136, v130, v131
	v_cvt_pk_bf16_f32 v137, v132, v133
	global_store_dwordx4 v164, v[134:137], s[100:101] offset:256 sc1
	s_add_u32 s100, s100, s14
	s_addc_u32 s101, s101, 0
	v_max_f32_e32 v126, 0, v126
	v_max_f32_e32 v127, 0, v127
	v_max_f32_e32 v128, 0, v128
	v_max_f32_e32 v129, 0, v129
	v_max_f32_e32 v122, 0, v122
	v_max_f32_e32 v123, 0, v123
	v_max_f32_e32 v124, 0, v124
	v_max_f32_e32 v125, 0, v125
	v_mul_f32_e32 v126, v126, v126
	v_mul_f32_e32 v127, v127, v127
	v_mul_f32_e32 v128, v128, v128
	v_mul_f32_e32 v129, v129, v129
	v_mul_f32_e32 v122, v122, v122
	v_mul_f32_e32 v123, v123, v123
	v_mul_f32_e32 v124, v124, v124
	v_mul_f32_e32 v125, v125, v125
	v_cvt_pk_bf16_f32 v126, v126, v127
	v_cvt_pk_bf16_f32 v127, v128, v129
	v_cvt_pk_bf16_f32 v128, v122, v123
	v_cvt_pk_bf16_f32 v129, v124, v125
	global_store_dwordx4 v164, v[126:129], s[100:101] sc1
	v_max_f32_e32 v118, 0, v118
	v_max_f32_e32 v119, 0, v119
	v_max_f32_e32 v120, 0, v120
	v_max_f32_e32 v121, 0, v121
	v_max_f32_e32 v114, 0, v114
	v_max_f32_e32 v115, 0, v115
	v_max_f32_e32 v116, 0, v116
	v_max_f32_e32 v117, 0, v117
	v_mul_f32_e32 v118, v118, v118
	v_mul_f32_e32 v119, v119, v119
	v_mul_f32_e32 v120, v120, v120
	v_mul_f32_e32 v121, v121, v121
	v_mul_f32_e32 v114, v114, v114
	v_mul_f32_e32 v115, v115, v115
	v_mul_f32_e32 v116, v116, v116
	v_mul_f32_e32 v117, v117, v117
	v_cvt_pk_bf16_f32 v118, v118, v119
	v_cvt_pk_bf16_f32 v119, v120, v121
	v_cvt_pk_bf16_f32 v120, v114, v115
	v_cvt_pk_bf16_f32 v121, v116, v117
	global_store_dwordx4 v164, v[118:121], s[100:101] offset:256 sc1
	s_add_u32 s100, s100, s14
	s_addc_u32 s101, s101, 0
	v_max_f32_e32 v110, 0, v110
	v_max_f32_e32 v111, 0, v111
	v_max_f32_e32 v112, 0, v112
	v_max_f32_e32 v113, 0, v113
	v_max_f32_e32 v106, 0, v106
	v_max_f32_e32 v107, 0, v107
	v_max_f32_e32 v108, 0, v108
	v_max_f32_e32 v109, 0, v109
	v_mul_f32_e32 v110, v110, v110
	v_mul_f32_e32 v111, v111, v111
	v_mul_f32_e32 v112, v112, v112
	v_mul_f32_e32 v113, v113, v113
	v_mul_f32_e32 v106, v106, v106
	v_mul_f32_e32 v107, v107, v107
	v_mul_f32_e32 v108, v108, v108
	v_mul_f32_e32 v109, v109, v109
	v_cvt_pk_bf16_f32 v110, v110, v111
	v_cvt_pk_bf16_f32 v111, v112, v113
	v_cvt_pk_bf16_f32 v112, v106, v107
	v_cvt_pk_bf16_f32 v113, v108, v109
	global_store_dwordx4 v164, v[110:113], s[100:101] sc1
	v_max_f32_e32 v102, 0, v102
	v_max_f32_e32 v103, 0, v103
	v_max_f32_e32 v104, 0, v104
	v_max_f32_e32 v105, 0, v105
	v_max_f32_e32 v98, 0, v98
	v_max_f32_e32 v99, 0, v99
	v_max_f32_e32 v100, 0, v100
	v_max_f32_e32 v101, 0, v101
	v_mul_f32_e32 v102, v102, v102
	v_mul_f32_e32 v103, v103, v103
	v_mul_f32_e32 v104, v104, v104
	v_mul_f32_e32 v105, v105, v105
	v_mul_f32_e32 v98, v98, v98
	v_mul_f32_e32 v99, v99, v99
	v_mul_f32_e32 v100, v100, v100
	v_mul_f32_e32 v101, v101, v101
	v_cvt_pk_bf16_f32 v102, v102, v103
	v_cvt_pk_bf16_f32 v103, v104, v105
	v_cvt_pk_bf16_f32 v104, v98, v99
	v_cvt_pk_bf16_f32 v105, v100, v101
	global_store_dwordx4 v164, v[102:105], s[100:101] offset:256 sc1
	s_add_u32 s100, s100, s14
	s_addc_u32 s101, s101, 0
	v_max_f32_e32 v94, 0, v94
	v_max_f32_e32 v95, 0, v95
	v_max_f32_e32 v96, 0, v96
	v_max_f32_e32 v97, 0, v97
	v_max_f32_e32 v90, 0, v90
	v_max_f32_e32 v91, 0, v91
	v_max_f32_e32 v92, 0, v92
	v_max_f32_e32 v93, 0, v93
	v_mul_f32_e32 v94, v94, v94
	v_mul_f32_e32 v95, v95, v95
	v_mul_f32_e32 v96, v96, v96
	v_mul_f32_e32 v97, v97, v97
	v_mul_f32_e32 v90, v90, v90
	v_mul_f32_e32 v91, v91, v91
	v_mul_f32_e32 v92, v92, v92
	v_mul_f32_e32 v93, v93, v93
	v_cvt_pk_bf16_f32 v94, v94, v95
	v_cvt_pk_bf16_f32 v95, v96, v97
	v_cvt_pk_bf16_f32 v96, v90, v91
	v_cvt_pk_bf16_f32 v97, v92, v93
	global_store_dwordx4 v164, v[94:97], s[100:101] sc1
	v_max_f32_e32 v70, 0, v70
	v_max_f32_e32 v71, 0, v71
	v_max_f32_e32 v72, 0, v72
	v_max_f32_e32 v73, 0, v73
	v_max_f32_e32 v66, 0, v66
	v_max_f32_e32 v67, 0, v67
	v_max_f32_e32 v68, 0, v68
	v_max_f32_e32 v69, 0, v69
	v_mul_f32_e32 v70, v70, v70
	v_mul_f32_e32 v71, v71, v71
; __device__ __forceinline__ unsigned cvt_pk_bf16(float lo, float hi) { unsigned r; asm volatile("v_cvt_pk_bf16_f32 %0, %1, %2" : "=v"(r) : "v"(lo), "v"(hi)); return r; }
;     __device__ __forceinline__ void operator()(const f32x4 (&acc)[2][2][4][2], const Unit& u, int wr, int wc, int fr, int fq) const {
;     ...
;             for (int m = 0; m < 4; ++m) { bf16_t* rowp = O + (size_t)(row0 + ai * HALF + m * 16) * ldc + col0;
; #pragma unroll
;                 for (int bj = 0; bj < 2; ++bj) { f32x4 v0 = acc[ai][bj][m][0], v1 = acc[ai][bj][m][1];
;                     if (gate) { v0 = v0 * gv[bj][0]; v1 = v1 * gv[bj][1]; }
;                     if (act == 1) {
; #pragma unroll
;                         for (int e = 0; e < 4; ++e) { float a = fmaxf(v0[e], 0.f), b = fmaxf(v1[e], 0.f); v0[e] = a * a; v1[e] = b * b; } }
;                     u32x4 w; w.x = cvt_pk_bf16(v0[0], v0[1]); w.y = cvt_pk_bf16(v0[2], v0[3]); w.z = cvt_pk_bf16(v1[0], v1[1]); w.w = cvt_pk_bf16(v1[2], v1[3]);
;                     *(u32x4*)(rowp + bj * HALF) = w; } }
	v_mul_f32_e32 v72, v72, v72
	v_mul_f32_e32 v73, v73, v73
	v_mul_f32_e32 v66, v66, v66
	v_mul_f32_e32 v67, v67, v67
	v_mul_f32_e32 v68, v68, v68
	v_mul_f32_e32 v69, v69, v69
	v_cvt_pk_bf16_f32 v70, v70, v71
	v_cvt_pk_bf16_f32 v71, v72, v73
	v_cvt_pk_bf16_f32 v72, v66, v67
	v_cvt_pk_bf16_f32 v73, v68, v69
	global_store_dwordx4 v164, v[70:73], s[100:101] offset:256 sc1
	s_add_u32 s100, s100, s15
	s_addc_u32 s101, s101, 0
	v_max_f32_e32 v62, 0, v62
	v_max_f32_e32 v63, 0, v63
	v_max_f32_e32 v64, 0, v64
	v_max_f32_e32 v65, 0, v65
	v_max_f32_e32 v58, 0, v58
	v_max_f32_e32 v59, 0, v59
	v_max_f32_e32 v60, 0, v60
	v_max_f32_e32 v61, 0, v61
	v_mul_f32_e32 v62, v62, v62
	v_mul_f32_e32 v63, v63, v63
	v_mul_f32_e32 v64, v64, v64
	v_mul_f32_e32 v65, v65, v65
	v_mul_f32_e32 v58, v58, v58
	v_mul_f32_e32 v59, v59, v59
	v_mul_f32_e32 v60, v60, v60
	v_mul_f32_e32 v61, v61, v61
	v_cvt_pk_bf16_f32 v62, v62, v63
	v_cvt_pk_bf16_f32 v63, v64, v65
	v_cvt_pk_bf16_f32 v64, v58, v59
	v_cvt_pk_bf16_f32 v65, v60, v61
	global_store_dwordx4 v164, v[62:65], s[100:101] sc1
	v_max_f32_e32 v54, 0, v54
	v_max_f32_e32 v55, 0, v55
	v_max_f32_e32 v56, 0, v56
	v_max_f32_e32 v57, 0, v57
	v_max_f32_e32 v50, 0, v50
	v_max_f32_e32 v51, 0, v51
	v_max_f32_e32 v52, 0, v52
	v_max_f32_e32 v53, 0, v53
	v_mul_f32_e32 v54, v54, v54
	v_mul_f32_e32 v55, v55, v55
	v_mul_f32_e32 v56, v56, v56
	v_mul_f32_e32 v57, v57, v57
	v_mul_f32_e32 v50, v50, v50
	v_mul_f32_e32 v51, v51, v51
	v_mul_f32_e32 v52, v52, v52
	v_mul_f32_e32 v53, v53, v53
	v_cvt_pk_bf16_f32 v54, v54, v55
	v_cvt_pk_bf16_f32 v55, v56, v57
	v_cvt_pk_bf16_f32 v56, v50, v51
	v_cvt_pk_bf16_f32 v57, v52, v53
	global_store_dwordx4 v164, v[54:57], s[100:101] offset:256 sc1
	s_add_u32 s100, s100, s14
	s_addc_u32 s101, s101, 0
	v_max_f32_e32 v46, 0, v46
	v_max_f32_e32 v47, 0, v47
	v_max_f32_e32 v48, 0, v48
	v_max_f32_e32 v49, 0, v49
	v_max_f32_e32 v42, 0, v42
	v_max_f32_e32 v43, 0, v43
	v_max_f32_e32 v44, 0, v44
	v_max_f32_e32 v45, 0, v45
	v_mul_f32_e32 v46, v46, v46
	v_mul_f32_e32 v47, v47, v47
	v_mul_f32_e32 v48, v48, v48
	v_mul_f32_e32 v49, v49, v49
	v_mul_f32_e32 v42, v42, v42
	v_mul_f32_e32 v43, v43, v43
	v_mul_f32_e32 v44, v44, v44
	v_mul_f32_e32 v45, v45, v45
	v_cvt_pk_bf16_f32 v46, v46, v47
	v_cvt_pk_bf16_f32 v47, v48, v49
	v_cvt_pk_bf16_f32 v48, v42, v43
	v_cvt_pk_bf16_f32 v49, v44, v45
	global_store_dwordx4 v164, v[46:49], s[100:101] sc1
	v_max_f32_e32 v38, 0, v38
	v_max_f32_e32 v39, 0, v39
	v_max_f32_e32 v40, 0, v40
	v_max_f32_e32 v41, 0, v41
	v_max_f32_e32 v34, 0, v34
	v_max_f32_e32 v35, 0, v35
	v_max_f32_e32 v36, 0, v36
	v_max_f32_e32 v37, 0, v37
	v_mul_f32_e32 v38, v38, v38
	v_mul_f32_e32 v39, v39, v39
	v_mul_f32_e32 v40, v40, v40
	v_mul_f32_e32 v41, v41, v41
	v_mul_f32_e32 v34, v34, v34
	v_mul_f32_e32 v35, v35, v35
	v_mul_f32_e32 v36, v36, v36
	v_mul_f32_e32 v37, v37, v37
	v_cvt_pk_bf16_f32 v38, v38, v39
	v_cvt_pk_bf16_f32 v39, v40, v41
	v_cvt_pk_bf16_f32 v40, v34, v35
	v_cvt_pk_bf16_f32 v41, v36, v37
	global_store_dwordx4 v164, v[38:41], s[100:101] offset:256 sc1
	s_add_u32 s100, s100, s14
	s_addc_u32 s101, s101, 0
	v_max_f32_e32 v30, 0, v30
	v_max_f32_e32 v31, 0, v31
	v_max_f32_e32 v32, 0, v32
	v_max_f32_e32 v33, 0, v33
	v_max_f32_e32 v26, 0, v26
	v_max_f32_e32 v27, 0, v27
	v_max_f32_e32 v28, 0, v28
	v_max_f32_e32 v29, 0, v29
	v_mul_f32_e32 v30, v30, v30
	v_mul_f32_e32 v31, v31, v31
	v_mul_f32_e32 v32, v32, v32
	v_mul_f32_e32 v33, v33, v33
	v_mul_f32_e32 v26, v26, v26
	v_mul_f32_e32 v27, v27, v27
	v_mul_f32_e32 v28, v28, v28
	v_mul_f32_e32 v29, v29, v29
	v_cvt_pk_bf16_f32 v30, v30, v31
	v_cvt_pk_bf16_f32 v31, v32, v33
	v_cvt_pk_bf16_f32 v32, v26, v27
	v_cvt_pk_bf16_f32 v33, v28, v29
	global_store_dwordx4 v164, v[30:33], s[100:101] sc1
	v_max_f32_e32 v22, 0, v22
	v_max_f32_e32 v23, 0, v23
	v_max_f32_e32 v24, 0, v24
	v_max_f32_e32 v25, 0, v25
	v_max_f32_e32 v18, 0, v18
	v_max_f32_e32 v19, 0, v19
	v_max_f32_e32 v20, 0, v20
	v_max_f32_e32 v21, 0, v21
	v_mul_f32_e32 v22, v22, v22
	v_mul_f32_e32 v23, v23, v23
	v_mul_f32_e32 v24, v24, v24
	v_mul_f32_e32 v25, v25, v25
	v_mul_f32_e32 v18, v18, v18
	v_mul_f32_e32 v19, v19, v19
	v_mul_f32_e32 v20, v20, v20
	v_mul_f32_e32 v21, v21, v21
	v_cvt_pk_bf16_f32 v22, v22, v23
	v_cvt_pk_bf16_f32 v23, v24, v25
	v_cvt_pk_bf16_f32 v24, v18, v19
	v_cvt_pk_bf16_f32 v25, v20, v21
	global_store_dwordx4 v164, v[22:25], s[100:101] offset:256 sc1
	s_add_u32 s100, s100, s14
	s_addc_u32 s101, s101, 0
	v_max_f32_e32 v14, 0, v14
	v_max_f32_e32 v15, 0, v15
	v_max_f32_e32 v16, 0, v16
	v_max_f32_e32 v17, 0, v17
	v_max_f32_e32 v10, 0, v10
	v_max_f32_e32 v11, 0, v11
	v_max_f32_e32 v12, 0, v12
	v_max_f32_e32 v13, 0, v13
	v_mul_f32_e32 v14, v14, v14
	v_mul_f32_e32 v15, v15, v15
	v_mul_f32_e32 v16, v16, v16
	v_mul_f32_e32 v17, v17, v17
	v_mul_f32_e32 v10, v10, v10
	v_mul_f32_e32 v11, v11, v11
	v_mul_f32_e32 v12, v12, v12
	v_mul_f32_e32 v13, v13, v13
	v_cvt_pk_bf16_f32 v14, v14, v15
	v_cvt_pk_bf16_f32 v15, v16, v17
	v_cvt_pk_bf16_f32 v16, v10, v11
	v_cvt_pk_bf16_f32 v17, v12, v13
	global_store_dwordx4 v164, v[14:17], s[100:101] sc1
	v_max_f32_e32 v6, 0, v6
	v_max_f32_e32 v7, 0, v7
	v_max_f32_e32 v8, 0, v8
	v_max_f32_e32 v9, 0, v9
	v_max_f32_e32 v2, 0, v2
	v_max_f32_e32 v3, 0, v3
	v_max_f32_e32 v4, 0, v4
	v_max_f32_e32 v5, 0, v5
	v_mul_f32_e32 v6, v6, v6
	v_mul_f32_e32 v7, v7, v7
	v_mul_f32_e32 v8, v8, v8
	v_mul_f32_e32 v9, v9, v9
	v_mul_f32_e32 v2, v2, v2
	v_mul_f32_e32 v3, v3, v3
	v_mul_f32_e32 v4, v4, v4
	v_mul_f32_e32 v5, v5, v5
	v_cvt_pk_bf16_f32 v6, v6, v7
	v_cvt_pk_bf16_f32 v7, v8, v9
	v_cvt_pk_bf16_f32 v8, v2, v3
	v_cvt_pk_bf16_f32 v9, v4, v5
	global_store_dwordx4 v164, v[6:9], s[100:101] offset:256 sc1
	s_andn2_b64 vcc, exec, s[42:43]
	s_mov_b64 s[14:15], -1
	s_branch .Lepi_join
; __device__ __forceinline__ unsigned cvt_pk_bf16(float lo, float hi) { unsigned r; asm volatile("v_cvt_pk_bf16_f32 %0, %1, %2" : "=v"(r) : "v"(lo), "v"(hi)); return r; }
;     __device__ __forceinline__ void operator()(const f32x4 (&acc)[2][2][4][2], const Unit& u, int wr, int wc, int fr, int fq) const {
;     ...
;             for (int m = 0; m < 4; ++m) { bf16_t* rowp = O + (size_t)(row0 + ai * HALF + m * 16) * ldc + col0;
; #pragma unroll
;                 for (int bj = 0; bj < 2; ++bj) { f32x4 v0 = acc[ai][bj][m][0], v1 = acc[ai][bj][m][1];
;                     if (gate) { v0 = v0 * gv[bj][0]; v1 = v1 * gv[bj][1]; }
;                     if (act == 1) {
; #pragma unroll
;                         for (int e = 0; e < 4; ++e) { float a = fmaxf(v0[e], 0.f), b = fmaxf(v1[e], 0.f); v0[e] = a * a; v1[e] = b * b; } }
;                     u32x4 w; w.x = cvt_pk_bf16(v0[0], v0[1]); w.y = cvt_pk_bf16(v0[2], v0[3]); w.z = cvt_pk_bf16(v1[0], v1[1]); w.w = cvt_pk_bf16(v1[2], v1[3]);
;                     *(u32x4*)(rowp + bj * HALF) = w; } }
.Lepi_lean_noact:
	v_cvt_pk_bf16_f32 v142, v142, v143
	v_cvt_pk_bf16_f32 v143, v144, v145
	v_cvt_pk_bf16_f32 v144, v138, v139
	v_cvt_pk_bf16_f32 v145, v140, v141
	global_store_dwordx4 v164, v[142:145], s[100:101] sc1
	v_cvt_pk_bf16_f32 v134, v134, v135
	v_cvt_pk_bf16_f32 v135, v136, v137
	v_cvt_pk_bf16_f32 v136, v130, v131
	v_cvt_pk_bf16_f32 v137, v132, v133
	global_store_dwordx4 v164, v[134:137], s[100:101] offset:256 sc1
	s_add_u32 s100, s100, s14
	s_addc_u32 s101, s101, 0
	v_cvt_pk_bf16_f32 v126, v126, v127
	v_cvt_pk_bf16_f32 v127, v128, v129
	v_cvt_pk_bf16_f32 v128, v122, v123
	v_cvt_pk_bf16_f32 v129, v124, v125
	global_store_dwordx4 v164, v[126:129], s[100:101] sc1
	v_cvt_pk_bf16_f32 v118, v118, v119
	v_cvt_pk_bf16_f32 v119, v120, v121
	v_cvt_pk_bf16_f32 v120, v114, v115
	v_cvt_pk_bf16_f32 v121, v116, v117
	global_store_dwordx4 v164, v[118:121], s[100:101] offset:256 sc1
	s_add_u32 s100, s100, s14
	s_addc_u32 s101, s101, 0
	v_cvt_pk_bf16_f32 v110, v110, v111
	v_cvt_pk_bf16_f32 v111, v112, v113
	v_cvt_pk_bf16_f32 v112, v106, v107
	v_cvt_pk_bf16_f32 v113, v108, v109
	global_store_dwordx4 v164, v[110:113], s[100:101] sc1
	v_cvt_pk_bf16_f32 v102, v102, v103
	v_cvt_pk_bf16_f32 v103, v104, v105
	v_cvt_pk_bf16_f32 v104, v98, v99
	v_cvt_pk_bf16_f32 v105, v100, v101
	global_store_dwordx4 v164, v[102:105], s[100:101] offset:256 sc1
	s_add_u32 s100, s100, s14
	s_addc_u32 s101, s101, 0
	v_cvt_pk_bf16_f32 v94, v94, v95
	v_cvt_pk_bf16_f32 v95, v96, v97
	v_cvt_pk_bf16_f32 v96, v90, v91
	v_cvt_pk_bf16_f32 v97, v92, v93
	global_store_dwordx4 v164, v[94:97], s[100:101] sc1
	v_cvt_pk_bf16_f32 v70, v70, v71
	v_cvt_pk_bf16_f32 v71, v72, v73
	v_cvt_pk_bf16_f32 v72, v66, v67
	v_cvt_pk_bf16_f32 v73, v68, v69
	global_store_dwordx4 v164, v[70:73], s[100:101] offset:256 sc1
	s_add_u32 s100, s100, s15
	s_addc_u32 s101, s101, 0
	v_cvt_pk_bf16_f32 v62, v62, v63
	v_cvt_pk_bf16_f32 v63, v64, v65
	v_cvt_pk_bf16_f32 v64, v58, v59
	v_cvt_pk_bf16_f32 v65, v60, v61
	global_store_dwordx4 v164, v[62:65], s[100:101] sc1
	v_cvt_pk_bf16_f32 v54, v54, v55
	v_cvt_pk_bf16_f32 v55, v56, v57
	v_cvt_pk_bf16_f32 v56, v50, v51
	v_cvt_pk_bf16_f32 v57, v52, v53
	global_store_dwordx4 v164, v[54:57], s[100:101] offset:256 sc1
	s_add_u32 s100, s100, s14
	s_addc_u32 s101, s101, 0
	v_cvt_pk_bf16_f32 v46, v46, v47
	v_cvt_pk_bf16_f32 v47, v48, v49
	v_cvt_pk_bf16_f32 v48, v42, v43
	v_cvt_pk_bf16_f32 v49, v44, v45
	global_store_dwordx4 v164, v[46:49], s[100:101] sc1
	v_cvt_pk_bf16_f32 v38, v38, v39
	v_cvt_pk_bf16_f32 v39, v40, v41
	v_cvt_pk_bf16_f32 v40, v34, v35
	v_cvt_pk_bf16_f32 v41, v36, v37
	global_store_dwordx4 v164, v[38:41], s[100:101] offset:256 sc1
	s_add_u32 s100, s100, s14
	s_addc_u32 s101, s101, 0
	v_cvt_pk_bf16_f32 v30, v30, v31
	v_cvt_pk_bf16_f32 v31, v32, v33
	v_cvt_pk_bf16_f32 v32, v26, v27
	v_cvt_pk_bf16_f32 v33, v28, v29
	global_store_dwordx4 v164, v[30:33], s[100:101] sc1
	v_cvt_pk_bf16_f32 v22, v22, v23
	v_cvt_pk_bf16_f32 v23, v24, v25
	v_cvt_pk_bf16_f32 v24, v18, v19
	v_cvt_pk_bf16_f32 v25, v20, v21
	global_store_dwordx4 v164, v[22:25], s[100:101] offset:256 sc1
	s_add_u32 s100, s100, s14
	s_addc_u32 s101, s101, 0
	v_cvt_pk_bf16_f32 v14, v14, v15
	v_cvt_pk_bf16_f32 v15, v16, v17
	v_cvt_pk_bf16_f32 v16, v10, v11
	v_cvt_pk_bf16_f32 v17, v12, v13
	global_store_dwordx4 v164, v[14:17], s[100:101] sc1
	v_cvt_pk_bf16_f32 v6, v6, v7
	v_cvt_pk_bf16_f32 v7, v8, v9
	v_cvt_pk_bf16_f32 v8, v2, v3
	v_cvt_pk_bf16_f32 v9, v4, v5
	global_store_dwordx4 v164, v[6:9], s[100:101] offset:256 sc1
	s_andn2_b64 vcc, exec, s[42:43]
	s_mov_b64 s[14:15], -1
	s_branch .Lepi_join

; __device__ __forceinline__ float bflo(unsigned w) { return __uint_as_float(w << 16); }
; __device__ __forceinline__ float bfhi(unsigned w) { return __uint_as_float(w & 0xffff0000u); }
; __device__ __forceinline__ unsigned pk2(float lo, float hi) { return pg8::cvt_pk_bf16(lo, hi); }
; __global__ void __launch_bounds__(512, 2) fwd_megakernel(Args args) {
;     ...
;                 if (ya) {
; #pragma unroll
;                     for (int j = 0; j < 4; ++j) { const u32x2 y = *(const u32x2*)(ya + (size_t)m * 1024 + 4 * lane + 256 * j); v[j] = v[j] + (f32x4){bflo(y.x), bfhi(y.x), bflo(y.y), bfhi(y.y)}; } }
;                 if (yb) {
; #pragma unroll
;                     for (int j = 0; j < 4; ++j) { const u32x2 y = *(const u32x2*)(yb + (size_t)m * 1024 + 4 * lane + 256 * j); v[j] = v[j] + (f32x4){bflo(y.x), bfhi(y.x), bflo(y.y), bfhi(y.y)}; } }
; #pragma unroll
;                 for (int j = 0; j < 4; ++j) ss += (v[j].x * v[j].x + v[j].y * v[j].y) + (v[j].z * v[j].z + v[j].w * v[j].w);
;                 if (wx) { float* dst = (m < M_LAT) ? xlat + (size_t)m * 1024 : xctx + (size_t)(m - M_LAT) * 1024;
; #pragma unroll
;                     for (int j = 0; j < 4; ++j) *(f32x4*)(dst + 4 * lane + 256 * j) = v[j]; }
;                 const float rstd = 1.0f / sqrtf(wave_sum(ss) * (1.f / 1024.f) + NEPS);
;                 const float* mc = modl + cond * 6144;
; #pragma unroll
;                 for (int j = 0; j < 4; ++j) { const int col = 4 * lane + 256 * j;
;                     const f32x4 gv = *(const f32x4*)(gvec + col), sc = *(const f32x4*)(mc + sc_off + col), sh = *(const f32x4*)(mc + sh_off + col);
;                     const f32x4 hv = (v[j] * rstd) * gv * (sc + 1.0f) + sh;
;                     u32x2 o; o.x = pk2(hv.x, hv.y); o.y = pk2(hv.z, hv.w); *(u32x2*)(XNY + (size_t)m * 1024 + col) = o; }
.Lnrm_noadd_8:
	s_andn2_b64 vcc, exec, s[4:5]
	s_cbranch_vccnz .Lnrm_noadd_9
	v_lshlrev_b32_e32 v116, 16, v92
	v_and_b32_e32 v117, 0xffff0000, v92
	v_lshlrev_b32_e32 v118, 16, v93
	v_and_b32_e32 v119, 0xffff0000, v93
	v_lshlrev_b32_e32 v120, 16, v94
	v_and_b32_e32 v121, 0xffff0000, v94
	v_lshlrev_b32_e32 v122, 16, v95
	v_and_b32_e32 v123, 0xffff0000, v95
	v_lshlrev_b32_e32 v124, 16, v96
	v_and_b32_e32 v125, 0xffff0000, v96
	v_lshlrev_b32_e32 v126, 16, v97
	v_and_b32_e32 v127, 0xffff0000, v97
	v_lshlrev_b32_e32 v128, 16, v98
	v_and_b32_e32 v129, 0xffff0000, v98
	v_lshlrev_b32_e32 v130, 16, v99
	v_and_b32_e32 v131, 0xffff0000, v99
	v_pk_add_f32 v[14:15], v[14:15], v[116:117]
	v_pk_add_f32 v[16:17], v[16:17], v[118:119]
	v_pk_add_f32 v[10:11], v[10:11], v[120:121]
	v_pk_add_f32 v[12:13], v[12:13], v[122:123]
	v_pk_add_f32 v[6:7], v[6:7], v[124:125]
	v_pk_add_f32 v[8:9], v[8:9], v[126:127]
	v_pk_add_f32 v[2:3], v[2:3], v[128:129]
	v_pk_add_f32 v[4:5], v[4:5], v[130:131]
	s_add_i32 s30, s100, 0xffff8000
	s_cmp_lt_i32 s100, 0x8000
	s_cselect_b32 s12, s100, s30
	s_cselect_b32 s6, s56, s14
	s_cselect_b32 s7, s57, s15
	s_mov_b32 s13, 0
	s_lshl_b64 s[12:13], s[12:13], 12
	s_add_u32 s6, s6, s12
	s_addc_u32 s7, s7, s13
	global_store_dwordx4 v0, v[14:17], s[6:7] sc1
	global_store_dwordx4 v0, v[10:13], s[6:7] offset:1024 sc1
	global_store_dwordx4 v0, v[6:9], s[6:7] offset:2048 sc1
	global_store_dwordx4 v0, v[2:5], s[6:7] offset:3072 sc1
.Lnrm_noadd_9:
	v_mul_f32_e32 v25, v15, v15
	v_mul_f32_e32 v36, v17, v17
	v_fmac_f32_e32 v25, v14, v14
	v_fmac_f32_e32 v36, v16, v16
	v_add_f32_e32 v25, v25, v36
	v_mul_f32_e32 v36, v11, v11
	v_mul_f32_e32 v37, v13, v13
	v_fmac_f32_e32 v36, v10, v10
	v_fmac_f32_e32 v37, v12, v12
	v_add_f32_e32 v36, v36, v37
	v_add_f32_e32 v25, v25, v36
	v_mul_f32_e32 v36, v7, v7
	v_mul_f32_e32 v37, v9, v9
	v_fmac_f32_e32 v36, v6, v6
	v_fmac_f32_e32 v37, v8, v8
	v_add_f32_e32 v36, v36, v37
	v_add_f32_e32 v25, v25, v36
	v_mul_f32_e32 v36, v3, v3
	v_mul_f32_e32 v37, v5, v5
	v_fmac_f32_e32 v36, v2, v2
	v_fmac_f32_e32 v37, v4, v4
	v_add_f32_e32 v36, v36, v37
	v_add_f32_e32 v25, v25, v36
	ds_swizzle_b32 v38, v25 offset:swizzle(SWAP,1)
	s_mov_b32 s30, 0xf800000
	s_waitcnt lgkmcnt(0)
	v_add_f32_e32 v25, v25, v38
	ds_swizzle_b32 v38, v25 offset:swizzle(SWAP,2)
	s_waitcnt lgkmcnt(0)
	v_add_f32_e32 v25, v25, v38
	ds_swizzle_b32 v38, v25 offset:swizzle(SWAP,4)
	s_waitcnt lgkmcnt(0)
	v_add_f32_e32 v25, v25, v38
	ds_swizzle_b32 v38, v25 offset:swizzle(SWAP,8)
	s_waitcnt lgkmcnt(0)
	v_add_f32_e32 v25, v25, v38
	ds_swizzle_b32 v38, v25 offset:swizzle(SWAP,16)
	s_waitcnt lgkmcnt(0)
	v_add_f32_e32 v25, v25, v38
	v_mov_b32_e32 v38, v25
	s_nop 1
	v_permlane32_swap_b32_e32 v25, v38
	v_add_f32_e32 v25, v25, v38
	v_fmamk_f32 v25, v25, 0x3a800000, v215
	v_mul_f32_e32 v38, 0x4f800000, v25
	v_cmp_gt_f32_e32 vcc, s30, v25
	s_nop 1
	v_cndmask_b32_e32 v25, v25, v38, vcc
	v_sqrt_f32_e32 v38, v25
	s_nop 0
	v_add_u32_e32 v39, -1, v38
	v_add_u32_e32 v40, 1, v38
	v_fma_f32 v41, -v39, v38, v25
	v_fma_f32 v42, -v40, v38, v25
	v_cmp_ge_f32_e64 s[38:39], 0, v41
	s_nop 1
	v_cndmask_b32_e64 v38, v38, v39, s[38:39]
	v_cmp_lt_f32_e64 s[38:39], 0, v42
	s_nop 1
	v_cndmask_b32_e64 v38, v38, v40, s[38:39]
	v_mul_f32_e32 v39, 0x37800000, v38
	v_cndmask_b32_e32 v38, v38, v39, vcc
	v_cmp_class_f32_e32 vcc, v25, v216
	s_nop 1
	v_cndmask_b32_e32 v25, v38, v25, vcc
	v_div_scale_f32 v38, s[30:31], v25, v25, 1.0
	v_rcp_f32_e32 v39, v38
	v_div_scale_f32 v40, vcc, 1.0, v25, 1.0
	v_fma_f32 v41, -v38, v39, 1.0
	v_fmac_f32_e32 v39, v41, v39
	v_mul_f32_e32 v41, v40, v39
	v_fma_f32 v42, -v38, v41, v40
	v_fmac_f32_e32 v41, v42, v39
	v_fma_f32 v38, -v38, v41, v40
	v_div_fmas_f32 v38, v38, v39, v41
	v_div_fixup_f32 v38, v38, v25, 1.0
	v_pk_mul_f32 v[14:15], v[38:39], v[14:15] op_sel_hi:[0,1]
	v_pk_mul_f32 v[16:17], v[38:39], v[16:17] op_sel_hi:[0,1]
	v_pk_mul_f32 v[10:11], v[38:39], v[10:11] op_sel_hi:[0,1]
	v_pk_mul_f32 v[12:13], v[38:39], v[12:13] op_sel_hi:[0,1]
	v_pk_mul_f32 v[6:7], v[38:39], v[6:7] op_sel_hi:[0,1]
	v_pk_mul_f32 v[8:9], v[38:39], v[8:9] op_sel_hi:[0,1]
	v_pk_mul_f32 v[2:3], v[38:39], v[2:3] op_sel_hi:[0,1]
	v_pk_mul_f32 v[4:5], v[38:39], v[4:5] op_sel_hi:[0,1]
	v_pk_mul_f32 v[14:15], v[44:45], v[14:15]
	v_pk_mul_f32 v[16:17], v[46:47], v[16:17]
	v_pk_mul_f32 v[10:11], v[48:49], v[10:11]
	v_pk_mul_f32 v[12:13], v[50:51], v[12:13]
	v_pk_mul_f32 v[6:7], v[52:53], v[6:7]
	v_pk_mul_f32 v[8:9], v[54:55], v[8:9]
	v_pk_mul_f32 v[2:3], v[56:57], v[2:3]
	v_pk_mul_f32 v[4:5], v[58:59], v[4:5]
	v_pk_add_f32 v[60:61], v[60:61], 1.0 op_sel_hi:[1,0]
	v_pk_add_f32 v[62:63], v[62:63], 1.0 op_sel_hi:[1,0]
	v_pk_add_f32 v[64:65], v[64:65], 1.0 op_sel_hi:[1,0]
	v_pk_add_f32 v[66:67], v[66:67], 1.0 op_sel_hi:[1,0]
	v_pk_add_f32 v[68:69], v[68:69], 1.0 op_sel_hi:[1,0]
	v_pk_add_f32 v[70:71], v[70:71], 1.0 op_sel_hi:[1,0]
	v_pk_add_f32 v[72:73], v[72:73], 1.0 op_sel_hi:[1,0]
	v_pk_add_f32 v[74:75], v[74:75], 1.0 op_sel_hi:[1,0]
	v_pk_fma_f32 v[14:15], v[60:61], v[14:15], v[76:77]
	v_pk_fma_f32 v[16:17], v[62:63], v[16:17], v[78:79]
	v_pk_fma_f32 v[10:11], v[64:65], v[10:11], v[80:81]
	v_pk_fma_f32 v[12:13], v[66:67], v[12:13], v[82:83]
	v_pk_fma_f32 v[6:7], v[68:69], v[6:7], v[84:85]
	v_pk_fma_f32 v[8:9], v[70:71], v[8:9], v[86:87]
	v_pk_fma_f32 v[2:3], v[72:73], v[2:3], v[88:89]
	v_pk_fma_f32 v[4:5], v[74:75], v[4:5], v[90:91]
	v_cvt_pk_bf16_f32 v14, v14, v15
	v_cvt_pk_bf16_f32 v15, v16, v17
	v_cvt_pk_bf16_f32 v10, v10, v11
	v_cvt_pk_bf16_f32 v11, v12, v13
	v_cvt_pk_bf16_f32 v6, v6, v7
	v_cvt_pk_bf16_f32 v7, v8, v9
	v_cvt_pk_bf16_f32 v2, v2, v3
	v_cvt_pk_bf16_f32 v3, v4, v5
	global_store_dwordx2 v[34:35], v[14:15], off offset:-1536 sc1
	global_store_dwordx2 v[34:35], v[10:11], off offset:-1024 sc1
	global_store_dwordx2 v[34:35], v[6:7], off offset:-512 sc1
	global_store_dwordx2 v[34:35], v[2:3], off sc1
	s_cmp_lt_i32 s101, 0
	s_cbranch_scc1 .LBB0_465
	s_cmp_lt_i32 s26, s10
	s_cbranch_scc1 .Lnrm_ld_a
	s_mov_b32 s100, -1
	s_waitcnt vmcnt(0)
	s_branch .Lnrm_B

; __device__ __forceinline__ float bflo(unsigned w) { return __uint_as_float(w << 16); }
; __device__ __forceinline__ float bfhi(unsigned w) { return __uint_as_float(w & 0xffff0000u); }
; __device__ __forceinline__ unsigned pk2(float lo, float hi) { return pg8::cvt_pk_bf16(lo, hi); }
; __global__ void __launch_bounds__(512, 2) fwd_megakernel(Args args) {
;     ...
;                 if (ya) {
; #pragma unroll
;                     for (int j = 0; j < 4; ++j) { const u32x2 y = *(const u32x2*)(ya + (size_t)m * 1024 + 4 * lane + 256 * j); v[j] = v[j] + (f32x4){bflo(y.x), bfhi(y.x), bflo(y.y), bfhi(y.y)}; } }
;                 if (yb) {
; #pragma unroll
;                     for (int j = 0; j < 4; ++j) { const u32x2 y = *(const u32x2*)(yb + (size_t)m * 1024 + 4 * lane + 256 * j); v[j] = v[j] + (f32x4){bflo(y.x), bfhi(y.x), bflo(y.y), bfhi(y.y)}; } }
; #pragma unroll
;                 for (int j = 0; j < 4; ++j) ss += (v[j].x * v[j].x + v[j].y * v[j].y) + (v[j].z * v[j].z + v[j].w * v[j].w);
;                 if (wx) { float* dst = (m < M_LAT) ? xlat + (size_t)m * 1024 : xctx + (size_t)(m - M_LAT) * 1024;
; #pragma unroll
;                     for (int j = 0; j < 4; ++j) *(f32x4*)(dst + 4 * lane + 256 * j) = v[j]; }
;                 const float rstd = 1.0f / sqrtf(wave_sum(ss) * (1.f / 1024.f) + NEPS);
;                 const float* mc = modl + cond * 6144;
; #pragma unroll
;                 for (int j = 0; j < 4; ++j) { const int col = 4 * lane + 256 * j;
;                     const f32x4 gv = *(const f32x4*)(gvec + col), sc = *(const f32x4*)(mc + sc_off + col), sh = *(const f32x4*)(mc + sh_off + col);
;                     const f32x4 hv = (v[j] * rstd) * gv * (sc + 1.0f) + sh;
;                     u32x2 o; o.x = pk2(hv.x, hv.y); o.y = pk2(hv.z, hv.w); *(u32x2*)(XNY + (size_t)m * 1024 + col) = o; }
.Lnrm_noadd_15:
	s_andn2_b64 vcc, exec, s[4:5]
	s_cbranch_vccnz .Lnrm_noadd_16
	v_lshlrev_b32_e32 v116, 16, v160
	v_and_b32_e32 v117, 0xffff0000, v160
	v_lshlrev_b32_e32 v118, 16, v161
	v_and_b32_e32 v119, 0xffff0000, v161
	v_lshlrev_b32_e32 v120, 16, v162
	v_and_b32_e32 v121, 0xffff0000, v162
	v_lshlrev_b32_e32 v122, 16, v163
	v_and_b32_e32 v123, 0xffff0000, v163
	v_lshlrev_b32_e32 v124, 16, v164
	v_and_b32_e32 v125, 0xffff0000, v164
	v_lshlrev_b32_e32 v126, 16, v165
	v_and_b32_e32 v127, 0xffff0000, v165
	v_lshlrev_b32_e32 v128, 16, v166
	v_and_b32_e32 v129, 0xffff0000, v166
	v_lshlrev_b32_e32 v130, 16, v167
	v_and_b32_e32 v131, 0xffff0000, v167
	v_pk_add_f32 v[148:149], v[148:149], v[116:117]
	v_pk_add_f32 v[150:151], v[150:151], v[118:119]
	v_pk_add_f32 v[144:145], v[144:145], v[120:121]
	v_pk_add_f32 v[146:147], v[146:147], v[122:123]
	v_pk_add_f32 v[140:141], v[140:141], v[124:125]
	v_pk_add_f32 v[142:143], v[142:143], v[126:127]
	v_pk_add_f32 v[136:137], v[136:137], v[128:129]
	v_pk_add_f32 v[138:139], v[138:139], v[130:131]
	s_add_i32 s30, s101, 0xffff8000
	s_cmp_lt_i32 s101, 0x8000
	s_cselect_b32 s12, s101, s30
	s_cselect_b32 s6, s56, s14
	s_cselect_b32 s7, s57, s15
	s_mov_b32 s13, 0
	s_lshl_b64 s[12:13], s[12:13], 12
	s_add_u32 s6, s6, s12
	s_addc_u32 s7, s7, s13
	global_store_dwordx4 v0, v[148:151], s[6:7] sc1
	global_store_dwordx4 v0, v[144:147], s[6:7] offset:1024 sc1
	global_store_dwordx4 v0, v[140:143], s[6:7] offset:2048 sc1
	global_store_dwordx4 v0, v[136:139], s[6:7] offset:3072 sc1
.Lnrm_noadd_16:
	v_mul_f32_e32 v25, v149, v149
	v_mul_f32_e32 v36, v151, v151
	v_fmac_f32_e32 v25, v148, v148
	v_fmac_f32_e32 v36, v150, v150
	v_add_f32_e32 v25, v25, v36
	v_mul_f32_e32 v36, v145, v145
	v_mul_f32_e32 v37, v147, v147
	v_fmac_f32_e32 v36, v144, v144
	v_fmac_f32_e32 v37, v146, v146
	v_add_f32_e32 v36, v36, v37
	v_add_f32_e32 v25, v25, v36
	v_mul_f32_e32 v36, v141, v141
	v_mul_f32_e32 v37, v143, v143
	v_fmac_f32_e32 v36, v140, v140
	v_fmac_f32_e32 v37, v142, v142
	v_add_f32_e32 v36, v36, v37
	v_add_f32_e32 v25, v25, v36
	v_mul_f32_e32 v36, v137, v137
	v_mul_f32_e32 v37, v139, v139
	v_fmac_f32_e32 v36, v136, v136
	v_fmac_f32_e32 v37, v138, v138
	v_add_f32_e32 v36, v36, v37
	v_add_f32_e32 v25, v25, v36
	ds_swizzle_b32 v38, v25 offset:swizzle(SWAP,1)
	s_mov_b32 s30, 0xf800000
	s_waitcnt lgkmcnt(0)
	v_add_f32_e32 v25, v25, v38
	ds_swizzle_b32 v38, v25 offset:swizzle(SWAP,2)
	s_waitcnt lgkmcnt(0)
	v_add_f32_e32 v25, v25, v38
	ds_swizzle_b32 v38, v25 offset:swizzle(SWAP,4)
	s_waitcnt lgkmcnt(0)
	v_add_f32_e32 v25, v25, v38
	ds_swizzle_b32 v38, v25 offset:swizzle(SWAP,8)
	s_waitcnt lgkmcnt(0)
	v_add_f32_e32 v25, v25, v38
	ds_swizzle_b32 v38, v25 offset:swizzle(SWAP,16)
	s_waitcnt lgkmcnt(0)
	v_add_f32_e32 v25, v25, v38
	v_mov_b32_e32 v38, v25
	s_nop 1
	v_permlane32_swap_b32_e32 v25, v38
	v_add_f32_e32 v25, v25, v38
	v_fmamk_f32 v25, v25, 0x3a800000, v215
	v_mul_f32_e32 v38, 0x4f800000, v25
	v_cmp_gt_f32_e32 vcc, s30, v25
	s_nop 1
	v_cndmask_b32_e32 v25, v25, v38, vcc
	v_sqrt_f32_e32 v38, v25
	s_nop 0
	v_add_u32_e32 v39, -1, v38
	v_add_u32_e32 v40, 1, v38
	v_fma_f32 v41, -v39, v38, v25
	v_fma_f32 v42, -v40, v38, v25
	v_cmp_ge_f32_e64 s[38:39], 0, v41
	s_nop 1
	v_cndmask_b32_e64 v38, v38, v39, s[38:39]
	v_cmp_lt_f32_e64 s[38:39], 0, v42
	s_nop 1
	v_cndmask_b32_e64 v38, v38, v40, s[38:39]
	v_mul_f32_e32 v39, 0x37800000, v38
	v_cndmask_b32_e32 v38, v38, v39, vcc
	v_cmp_class_f32_e32 vcc, v25, v216
	s_nop 1
	v_cndmask_b32_e32 v25, v38, v25, vcc
	v_div_scale_f32 v38, s[30:31], v25, v25, 1.0
	v_rcp_f32_e32 v39, v38
	v_div_scale_f32 v40, vcc, 1.0, v25, 1.0
	v_fma_f32 v41, -v38, v39, 1.0
	v_fmac_f32_e32 v39, v41, v39
	v_mul_f32_e32 v41, v40, v39
	v_fma_f32 v42, -v38, v41, v40
	v_fmac_f32_e32 v41, v42, v39
	v_fma_f32 v38, -v38, v41, v40
	v_div_fmas_f32 v38, v38, v39, v41
	v_div_fixup_f32 v38, v38, v25, 1.0
	v_pk_mul_f32 v[148:149], v[38:39], v[148:149] op_sel_hi:[0,1]
	v_pk_mul_f32 v[150:151], v[38:39], v[150:151] op_sel_hi:[0,1]
	v_pk_mul_f32 v[144:145], v[38:39], v[144:145] op_sel_hi:[0,1]
	v_pk_mul_f32 v[146:147], v[38:39], v[146:147] op_sel_hi:[0,1]
	v_pk_mul_f32 v[140:141], v[38:39], v[140:141] op_sel_hi:[0,1]
	v_pk_mul_f32 v[142:143], v[38:39], v[142:143] op_sel_hi:[0,1]
	v_pk_mul_f32 v[136:137], v[38:39], v[136:137] op_sel_hi:[0,1]
	v_pk_mul_f32 v[138:139], v[38:39], v[138:139] op_sel_hi:[0,1]
	v_pk_mul_f32 v[148:149], v[44:45], v[148:149]
	v_pk_mul_f32 v[150:151], v[46:47], v[150:151]
	v_pk_mul_f32 v[144:145], v[48:49], v[144:145]
	v_pk_mul_f32 v[146:147], v[50:51], v[146:147]
	v_pk_mul_f32 v[140:141], v[52:53], v[140:141]
	v_pk_mul_f32 v[142:143], v[54:55], v[142:143]
	v_pk_mul_f32 v[136:137], v[56:57], v[136:137]
	v_pk_mul_f32 v[138:139], v[58:59], v[138:139]
	v_pk_add_f32 v[168:169], v[168:169], 1.0 op_sel_hi:[1,0]
	v_pk_add_f32 v[170:171], v[170:171], 1.0 op_sel_hi:[1,0]
	v_pk_add_f32 v[172:173], v[172:173], 1.0 op_sel_hi:[1,0]
	v_pk_add_f32 v[174:175], v[174:175], 1.0 op_sel_hi:[1,0]
	v_pk_add_f32 v[176:177], v[176:177], 1.0 op_sel_hi:[1,0]
	v_pk_add_f32 v[178:179], v[178:179], 1.0 op_sel_hi:[1,0]
	v_pk_add_f32 v[180:181], v[180:181], 1.0 op_sel_hi:[1,0]
	v_pk_add_f32 v[182:183], v[182:183], 1.0 op_sel_hi:[1,0]
	v_pk_fma_f32 v[148:149], v[168:169], v[148:149], v[184:185]
	v_pk_fma_f32 v[150:151], v[170:171], v[150:151], v[186:187]
	v_pk_fma_f32 v[144:145], v[172:173], v[144:145], v[188:189]
	v_pk_fma_f32 v[146:147], v[174:175], v[146:147], v[190:191]
	v_pk_fma_f32 v[140:141], v[176:177], v[140:141], v[192:193]
	v_pk_fma_f32 v[142:143], v[178:179], v[142:143], v[194:195]
	v_pk_fma_f32 v[136:137], v[180:181], v[136:137], v[196:197]
	v_pk_fma_f32 v[138:139], v[182:183], v[138:139], v[198:199]
	v_cvt_pk_bf16_f32 v148, v148, v149
	v_cvt_pk_bf16_f32 v149, v150, v151
	v_cvt_pk_bf16_f32 v144, v144, v145
	v_cvt_pk_bf16_f32 v145, v146, v147
	v_cvt_pk_bf16_f32 v140, v140, v141
	v_cvt_pk_bf16_f32 v141, v142, v143
	v_cvt_pk_bf16_f32 v136, v136, v137
	v_cvt_pk_bf16_f32 v137, v138, v139
	global_store_dwordx2 v[200:201], v[148:149], off offset:-1536 sc1
	global_store_dwordx2 v[200:201], v[144:145], off offset:-1024 sc1
	global_store_dwordx2 v[200:201], v[140:141], off offset:-512 sc1
	global_store_dwordx2 v[200:201], v[136:137], off sc1
	s_cmp_lt_i32 s100, 0
	s_cbranch_scc1 .LBB0_465
	s_cmp_lt_i32 s26, s10
	s_cbranch_scc1 .Lnrm_ld_b
	s_mov_b32 s101, -1
	s_waitcnt vmcnt(0)
	s_branch .Lnrm_A
